# conv row loads hoisted; grid barrier: last XCD leader bumps all per-XCC generation words directly (one release hop less)
# baseline (speedup 1.0000x reference)
.LBB0_104:
	s_or_b64 exec, exec, s[22:23]
	v_mov_b64_e32 v[2:3], s[20:21]
	s_orn2_b64 s[20:21], s[24:25], exec
	s_branch .LBB0_105
.Lsync_last_0:
	s_or_b64 exec, exec, s[12:13]
	s_add_u32 s100, s8, 0x17202400
	s_addc_u32 s101, s9, 0
	v_mov_b32_e32 v7, 0
	v_mov_b32_e32 v8, 1
	global_atomic_add v7, v8, s[100:101]
	global_atomic_add v7, v8, s[100:101] offset:256
	global_atomic_add v7, v8, s[100:101] offset:512
	global_atomic_add v7, v8, s[100:101] offset:768
	global_atomic_add v7, v8, s[100:101] offset:1024
	global_atomic_add v7, v8, s[100:101] offset:1280
	global_atomic_add v7, v8, s[100:101] offset:1536
	global_atomic_add v7, v8, s[100:101] offset:1792
	global_atomic_add v7, v8, s[100:101] offset:2048
	global_atomic_add v7, v8, s[100:101] offset:2304
	global_atomic_add v7, v8, s[100:101] offset:2560
	global_atomic_add v7, v8, s[100:101] offset:2816
	global_atomic_add v7, v8, s[100:101] offset:3072
	global_atomic_add v7, v8, s[100:101] offset:3328
	global_atomic_add v7, v8, s[100:101] offset:3584
	global_atomic_add v7, v8, s[100:101] offset:3840

.LBB0_107:
	s_or_b64 exec, exec, s[8:9]
	s_mov_b64 s[8:9], exec
	v_mbcnt_lo_u32_b32 v2, s8, 0
	v_mbcnt_hi_u32_b32 v2, s9, v2
	v_cmp_eq_u32_e32 vcc, 0, v2
	s_waitcnt vmcnt(0)
	s_and_saveexec_b64 s[12:13], vcc
	s_cbranch_execz .LBB0_109
	s_bcnt1_i32_b64 s3, s[8:9]
	v_mov_b32_e32 v2, 0x2000
	v_mov_b32_e32 v3, s3
.LBB0_109:
	s_or_b64 exec, exec, s[12:13]
	s_waitcnt vmcnt(0)

.LBB0_345:
	s_or_b64 exec, exec, s[12:13]
	v_lshl_add_u64 v[42:43], s[80:81], 0, v[32:33]
	v_lshl_add_u64 v[40:41], s[8:9], 0, v[32:33]
	v_lshl_add_u64 v[36:37], s[86:87], 0, v[32:33]
	v_mad_i64_i32 v[244:245], s[12:13], v38, s58, v[42:43]
	global_load_dwordx4 v[178:181], v[244:245], off nt
	v_mad_i64_i32 v[244:245], s[12:13], v38, s58, v[40:41]
	global_load_dwordx4 v[182:185], v[244:245], off nt
	v_add_u32_e32 v242, 1, v38
	v_mad_i64_i32 v[244:245], s[12:13], v242, s58, v[42:43]
	global_load_dwordx4 v[186:189], v[244:245], off nt
	v_mad_i64_i32 v[244:245], s[12:13], v242, s58, v[40:41]
	global_load_dwordx4 v[190:193], v[244:245], off nt
	v_add_u32_e32 v242, 2, v38
	v_mad_i64_i32 v[244:245], s[12:13], v242, s58, v[42:43]
	global_load_dwordx4 v[194:197], v[244:245], off nt
	v_mad_i64_i32 v[244:245], s[12:13], v242, s58, v[40:41]
	global_load_dwordx4 v[198:201], v[244:245], off nt
	v_add_u32_e32 v242, 3, v38
	v_mad_i64_i32 v[244:245], s[12:13], v242, s58, v[42:43]
	global_load_dwordx4 v[202:205], v[244:245], off nt
	v_mad_i64_i32 v[244:245], s[12:13], v242, s58, v[40:41]
	global_load_dwordx4 v[206:209], v[244:245], off nt
	v_add_u32_e32 v242, 4, v38
	v_mad_i64_i32 v[244:245], s[12:13], v242, s58, v[42:43]
	global_load_dwordx4 v[210:213], v[244:245], off nt
	v_mad_i64_i32 v[244:245], s[12:13], v242, s58, v[40:41]
	global_load_dwordx4 v[214:217], v[244:245], off nt
	v_add_u32_e32 v242, 5, v38
	v_mad_i64_i32 v[244:245], s[12:13], v242, s58, v[42:43]
	global_load_dwordx4 v[218:221], v[244:245], off nt
	v_mad_i64_i32 v[244:245], s[12:13], v242, s58, v[40:41]
	global_load_dwordx4 v[222:225], v[244:245], off nt
	v_add_u32_e32 v242, 6, v38
	v_mad_i64_i32 v[244:245], s[12:13], v242, s58, v[42:43]
	global_load_dwordx4 v[226:229], v[244:245], off nt
	v_mad_i64_i32 v[244:245], s[12:13], v242, s58, v[40:41]
	global_load_dwordx4 v[230:233], v[244:245], off nt
	v_add_u32_e32 v242, 7, v38
	v_mad_i64_i32 v[244:245], s[12:13], v242, s58, v[42:43]
	global_load_dwordx4 v[234:237], v[244:245], off nt
	v_mad_i64_i32 v[244:245], s[12:13], v242, s58, v[40:41]
	global_load_dwordx4 v[238:241], v[244:245], off nt
	v_mad_i64_i32 v[32:33], s[12:13], v38, s58, v[42:43]
	v_mad_i64_i32 v[32:33], s[12:13], v38, s58, v[40:41]
	s_waitcnt vmcnt(14)
	v_pk_mul_f32 v[64:65], v[22:23], v[48:49]
	v_ashrrev_i32_e32 v39, 31, v38
	v_pk_fma_f32 v[30:31], v[14:15], v[30:31], v[64:65]
	v_pk_mul_f32 v[64:65], v[6:7], v[44:45]
	v_or_b32_e32 v68, 2, v38
	v_pk_fma_f32 v[26:27], v[2:3], v[26:27], v[64:65]
	v_ashrrev_i32_e32 v69, 31, v68
	v_add_u32_e32 v35, s63, v35
	s_mov_b32 s5, 0x5ffff
	v_cmp_lt_i32_e32 vcc, s5, v35
	v_add_u32_e32 v34, s4, v34
	s_or_b64 s[90:91], vcc, s[90:91]
	v_lshlrev_b32_e32 v32, 16, v178
	v_and_b32_e32 v33, 0xffff0000, v178
	v_pk_fma_f32 v[30:31], v[18:19], v[32:33], v[30:31]
	v_lshlrev_b32_e32 v62, 16, v182
	v_and_b32_e32 v63, 0xffff0000, v182
	v_pk_mul_f32 v[62:63], v[30:31], v[62:63]
	v_lshlrev_b32_e32 v30, 16, v179
	v_and_b32_e32 v31, 0xffff0000, v179
	v_lshlrev_b32_e32 v54, 16, v183
	v_and_b32_e32 v55, 0xffff0000, v183
	v_pk_mul_f32 v[58:59], v[24:25], v[46:47]
	v_pk_mul_f32 v[66:67], v[22:23], v[32:33]
	v_pk_fma_f32 v[28:29], v[16:17], v[28:29], v[58:59]
	v_pk_fma_f32 v[48:49], v[14:15], v[48:49], v[66:67]
	v_pk_fma_f32 v[28:29], v[20:21], v[30:31], v[28:29]
	s_nop 0
	v_pk_mul_f32 v[58:59], v[28:29], v[54:55]
	v_lshlrev_b32_e32 v28, 16, v180
	v_and_b32_e32 v29, 0xffff0000, v180
	v_lshlrev_b32_e32 v54, 16, v184
	v_and_b32_e32 v55, 0xffff0000, v184
	v_pk_fma_f32 v[26:27], v[10:11], v[28:29], v[26:27]
	v_pk_mul_f32 v[66:67], v[6:7], v[28:29]
	v_pk_mul_f32 v[64:65], v[26:27], v[54:55]
	v_lshlrev_b32_e32 v26, 16, v181
	v_and_b32_e32 v27, 0xffff0000, v181
	v_pk_mul_f32 v[56:57], v[8:9], v[52:53]
	v_lshlrev_b32_e32 v54, 16, v185
	v_pk_fma_f32 v[50:51], v[4:5], v[50:51], v[56:57]
	v_and_b32_e32 v55, 0xffff0000, v185
	v_pk_fma_f32 v[50:51], v[12:13], v[26:27], v[50:51]
	v_cvt_pk_bf16_f32 v56, v64, v65
	v_pk_mul_f32 v[50:51], v[50:51], v[54:55]
	v_cvt_pk_bf16_f32 v54, v62, v63
	v_cvt_pk_bf16_f32 v57, v50, v51
	v_lshlrev_b64 v[50:51], 11, v[38:39]
	v_cvt_pk_bf16_f32 v55, v58, v59
	v_lshl_add_u64 v[50:51], v[36:37], 0, v[50:51]
	v_or_b32_e32 v62, 1, v38
	global_store_dwordx4 v[50:51], v[54:57], off
	v_mad_i64_i32 v[50:51], s[12:13], v62, s58, v[42:43]
	v_mad_i64_i32 v[50:51], s[12:13], v62, s58, v[40:41]
	v_pk_fma_f32 v[44:45], v[2:3], v[44:45], v[66:67]
	v_ashrrev_i32_e32 v63, 31, v62
	s_waitcnt vmcnt(14)
	v_lshlrev_b32_e32 v50, 16, v186
	v_and_b32_e32 v51, 0xffff0000, v186
	v_pk_fma_f32 v[48:49], v[18:19], v[50:51], v[48:49]
	s_waitcnt vmcnt(13)
	v_lshlrev_b32_e32 v64, 16, v190
	v_and_b32_e32 v65, 0xffff0000, v190
	v_pk_mul_f32 v[64:65], v[48:49], v[64:65]
	v_lshlrev_b32_e32 v48, 16, v187
	v_and_b32_e32 v49, 0xffff0000, v187
	v_lshlrev_b32_e32 v54, 16, v191
	v_and_b32_e32 v55, 0xffff0000, v191
	v_pk_mul_f32 v[58:59], v[24:25], v[30:31]
	s_nop 0
	v_pk_fma_f32 v[46:47], v[16:17], v[46:47], v[58:59]
	v_lshlrev_b32_e32 v58, 16, v192
	v_pk_fma_f32 v[46:47], v[20:21], v[48:49], v[46:47]
	v_and_b32_e32 v59, 0xffff0000, v192
	v_pk_mul_f32 v[54:55], v[46:47], v[54:55]
	v_lshlrev_b32_e32 v46, 16, v188
	v_and_b32_e32 v47, 0xffff0000, v188
	v_pk_fma_f32 v[44:45], v[10:11], v[46:47], v[44:45]
	v_lshlrev_b32_e32 v56, 16, v193
	v_pk_mul_f32 v[58:59], v[44:45], v[58:59]
	v_lshlrev_b32_e32 v44, 16, v189
	v_and_b32_e32 v45, 0xffff0000, v189
	v_and_b32_e32 v57, 0xffff0000, v193
	v_pk_mul_f32 v[60:61], v[8:9], v[26:27]
	s_nop 0
	v_pk_fma_f32 v[52:53], v[4:5], v[52:53], v[60:61]
	s_nop 0
	v_pk_fma_f32 v[52:53], v[12:13], v[44:45], v[52:53]
	s_nop 0
	v_pk_mul_f32 v[56:57], v[52:53], v[56:57]
	v_cvt_pk_bf16_f32 v53, v54, v55
	v_cvt_pk_bf16_f32 v55, v56, v57
	v_lshlrev_b64 v[56:57], 11, v[62:63]
	v_cvt_pk_bf16_f32 v52, v64, v65
	v_cvt_pk_bf16_f32 v54, v58, v59
	v_lshl_add_u64 v[56:57], v[36:37], 0, v[56:57]
	global_store_dwordx4 v[56:57], v[52:55], off
	s_nop 1
	v_mad_i64_i32 v[52:53], s[12:13], v68, s58, v[42:43]
	v_mad_i64_i32 v[52:53], s[12:13], v68, s58, v[40:41]
	v_pk_mul_f32 v[54:55], v[22:23], v[50:51]
	s_waitcnt vmcnt(13)
	v_lshlrev_b32_e32 v58, 16, v194
	v_and_b32_e32 v59, 0xffff0000, v194
	v_pk_fma_f32 v[32:33], v[14:15], v[32:33], v[54:55]
	v_pk_mul_f32 v[54:55], v[24:25], v[48:49]
	s_waitcnt vmcnt(12)
	v_lshlrev_b32_e32 v52, 16, v198
	v_and_b32_e32 v53, 0xffff0000, v198
	v_pk_fma_f32 v[32:33], v[18:19], v[58:59], v[32:33]
	v_lshlrev_b32_e32 v56, 16, v195
	v_and_b32_e32 v57, 0xffff0000, v195
	v_pk_fma_f32 v[30:31], v[16:17], v[30:31], v[54:55]
	v_pk_mul_f32 v[60:61], v[6:7], v[46:47]
	v_pk_mul_f32 v[32:33], v[32:33], v[52:53]
	v_lshlrev_b32_e32 v52, 16, v199
	v_and_b32_e32 v53, 0xffff0000, v199
	v_pk_fma_f32 v[30:31], v[20:21], v[56:57], v[30:31]
	v_lshlrev_b32_e32 v54, 16, v196
	v_and_b32_e32 v55, 0xffff0000, v196
	v_pk_fma_f32 v[28:29], v[2:3], v[28:29], v[60:61]
	v_pk_mul_f32 v[30:31], v[30:31], v[52:53]
	v_lshlrev_b32_e32 v52, 16, v200
	v_and_b32_e32 v53, 0xffff0000, v200
	v_pk_fma_f32 v[28:29], v[10:11], v[54:55], v[28:29]
	v_lshlrev_b32_e32 v60, 16, v201
	v_pk_mul_f32 v[28:29], v[28:29], v[52:53]
	v_lshlrev_b32_e32 v52, 16, v197
	v_and_b32_e32 v53, 0xffff0000, v197
	v_pk_mul_f32 v[62:63], v[8:9], v[44:45]
	v_and_b32_e32 v61, 0xffff0000, v201
	v_pk_fma_f32 v[26:27], v[4:5], v[26:27], v[62:63]
	v_cvt_pk_bf16_f32 v28, v28, v29
	v_pk_fma_f32 v[26:27], v[12:13], v[52:53], v[26:27]
	v_pk_mul_f32 v[64:65], v[22:23], v[58:59]
	v_pk_mul_f32 v[60:61], v[26:27], v[60:61]
	v_cvt_pk_bf16_f32 v27, v30, v31
	v_lshlrev_b64 v[30:31], 11, v[68:69]
	v_cvt_pk_bf16_f32 v26, v32, v33
	v_cvt_pk_bf16_f32 v29, v60, v61
	v_lshl_add_u64 v[30:31], v[36:37], 0, v[30:31]
	v_or_b32_e32 v68, 3, v38
	global_store_dwordx4 v[30:31], v[26:29], off
	v_pk_fma_f32 v[50:51], v[14:15], v[50:51], v[64:65]
	v_ashrrev_i32_e32 v69, 31, v68
	v_mad_i64_i32 v[26:27], s[12:13], v68, s58, v[42:43]
	v_mad_i64_i32 v[26:27], s[12:13], v68, s58, v[40:41]
	s_waitcnt vmcnt(12)
	v_lshlrev_b32_e32 v60, 16, v202
	v_and_b32_e32 v61, 0xffff0000, v202
	v_pk_fma_f32 v[50:51], v[18:19], v[60:61], v[50:51]
	s_waitcnt vmcnt(11)
	v_lshlrev_b32_e32 v62, 16, v206
	v_and_b32_e32 v63, 0xffff0000, v206
	v_pk_mul_f32 v[50:51], v[50:51], v[62:63]
	v_lshlrev_b32_e32 v62, 16, v203
	v_and_b32_e32 v63, 0xffff0000, v203
	v_pk_mul_f32 v[30:31], v[24:25], v[56:57]
	v_lshlrev_b32_e32 v26, 16, v207
	v_pk_fma_f32 v[30:31], v[16:17], v[48:49], v[30:31]
	v_pk_mul_f32 v[48:49], v[6:7], v[54:55]
	v_and_b32_e32 v27, 0xffff0000, v207
	v_pk_fma_f32 v[30:31], v[20:21], v[62:63], v[30:31]
	v_lshlrev_b32_e32 v64, 16, v204
	v_and_b32_e32 v65, 0xffff0000, v204
	v_pk_fma_f32 v[46:47], v[2:3], v[46:47], v[48:49]
	v_pk_mul_f32 v[30:31], v[30:31], v[26:27]
	v_lshlrev_b32_e32 v26, 16, v208
	v_and_b32_e32 v27, 0xffff0000, v208
	v_pk_fma_f32 v[46:47], v[10:11], v[64:65], v[46:47]
	v_lshlrev_b32_e32 v66, 16, v205
	v_pk_mul_f32 v[46:47], v[46:47], v[26:27]
	v_lshlrev_b32_e32 v26, 16, v209
	v_and_b32_e32 v27, 0xffff0000, v209
	v_pk_mul_f32 v[28:29], v[8:9], v[52:53]
	v_and_b32_e32 v67, 0xffff0000, v205
	v_pk_fma_f32 v[28:29], v[4:5], v[44:45], v[28:29]
	s_nop 0
	v_pk_fma_f32 v[28:29], v[12:13], v[66:67], v[28:29]
	s_nop 0
	v_pk_mul_f32 v[32:33], v[28:29], v[26:27]
	v_cvt_pk_bf16_f32 v27, v30, v31
	v_lshlrev_b64 v[30:31], 11, v[68:69]
	v_cvt_pk_bf16_f32 v26, v50, v51
	v_cvt_pk_bf16_f32 v28, v46, v47
	v_cvt_pk_bf16_f32 v29, v32, v33
	v_lshl_add_u64 v[30:31], v[36:37], 0, v[30:31]
	v_or_b32_e32 v68, 4, v38
	global_store_dwordx4 v[30:31], v[26:29], off
	v_ashrrev_i32_e32 v69, 31, v68
	s_nop 0
	v_mad_i64_i32 v[26:27], s[12:13], v68, s58, v[42:43]
	v_mad_i64_i32 v[26:27], s[12:13], v68, s58, v[40:41]
	v_pk_mul_f32 v[28:29], v[22:23], v[60:61]
	s_waitcnt vmcnt(11)
	v_lshlrev_b32_e32 v32, 16, v210
	v_and_b32_e32 v33, 0xffff0000, v210
	v_pk_fma_f32 v[28:29], v[14:15], v[58:59], v[28:29]
	s_waitcnt vmcnt(10)
	v_lshlrev_b32_e32 v26, 16, v214
	v_and_b32_e32 v27, 0xffff0000, v214
	v_pk_fma_f32 v[28:29], v[18:19], v[32:33], v[28:29]
	v_lshlrev_b32_e32 v30, 16, v211
	v_pk_mul_f32 v[58:59], v[28:29], v[26:27]
	v_pk_mul_f32 v[28:29], v[24:25], v[62:63]
	v_and_b32_e32 v31, 0xffff0000, v211
	v_pk_fma_f32 v[28:29], v[16:17], v[56:57], v[28:29]
	v_lshlrev_b32_e32 v26, 16, v215
	v_and_b32_e32 v27, 0xffff0000, v215
	v_pk_fma_f32 v[28:29], v[20:21], v[30:31], v[28:29]
	v_pk_mul_f32 v[44:45], v[6:7], v[64:65]
	v_pk_mul_f32 v[48:49], v[28:29], v[26:27]
	v_lshlrev_b32_e32 v28, 16, v212
	v_and_b32_e32 v29, 0xffff0000, v212
	v_pk_fma_f32 v[44:45], v[2:3], v[54:55], v[44:45]
	v_lshlrev_b32_e32 v26, 16, v216
	v_and_b32_e32 v27, 0xffff0000, v216
	v_pk_fma_f32 v[44:45], v[10:11], v[28:29], v[44:45]
	s_nop 0
	v_pk_mul_f32 v[54:55], v[44:45], v[26:27]
	v_lshlrev_b32_e32 v26, 16, v213
	v_and_b32_e32 v27, 0xffff0000, v213
	v_pk_mul_f32 v[46:47], v[8:9], v[66:67]
	v_lshlrev_b32_e32 v44, 16, v217
	v_pk_fma_f32 v[46:47], v[4:5], v[52:53], v[46:47]
	v_and_b32_e32 v45, 0xffff0000, v217
	v_pk_fma_f32 v[46:47], v[12:13], v[26:27], v[46:47]
	s_nop 0
	v_pk_mul_f32 v[50:51], v[46:47], v[44:45]
	v_cvt_pk_bf16_f32 v45, v48, v49
	v_lshlrev_b64 v[48:49], 11, v[68:69]
	v_cvt_pk_bf16_f32 v44, v58, v59
	v_cvt_pk_bf16_f32 v46, v54, v55
	v_cvt_pk_bf16_f32 v47, v50, v51
	v_lshl_add_u64 v[48:49], v[36:37], 0, v[48:49]
	v_or_b32_e32 v68, 5, v38
	global_store_dwordx4 v[48:49], v[44:47], off
	v_ashrrev_i32_e32 v69, 31, v68
	s_nop 0
	v_mad_i64_i32 v[44:45], s[12:13], v68, s58, v[42:43]
	v_mad_i64_i32 v[44:45], s[12:13], v68, s58, v[40:41]
	v_pk_mul_f32 v[46:47], v[22:23], v[32:33]
	s_waitcnt vmcnt(10)
	v_lshlrev_b32_e32 v50, 16, v218
	v_and_b32_e32 v51, 0xffff0000, v218
	v_pk_fma_f32 v[46:47], v[14:15], v[60:61], v[46:47]
	s_waitcnt vmcnt(9)
	v_lshlrev_b32_e32 v44, 16, v222
	v_and_b32_e32 v45, 0xffff0000, v222
	v_pk_fma_f32 v[46:47], v[18:19], v[50:51], v[46:47]
	v_lshlrev_b32_e32 v48, 16, v219
	v_pk_mul_f32 v[60:61], v[46:47], v[44:45]
	v_pk_mul_f32 v[46:47], v[24:25], v[30:31]
	v_and_b32_e32 v49, 0xffff0000, v219
	v_pk_fma_f32 v[46:47], v[16:17], v[62:63], v[46:47]
	v_lshlrev_b32_e32 v44, 16, v223
	v_and_b32_e32 v45, 0xffff0000, v223
	v_pk_fma_f32 v[46:47], v[20:21], v[48:49], v[46:47]
	v_pk_mul_f32 v[52:53], v[6:7], v[28:29]
	v_pk_mul_f32 v[56:57], v[46:47], v[44:45]
	v_lshlrev_b32_e32 v46, 16, v220
	v_and_b32_e32 v47, 0xffff0000, v220
	v_pk_fma_f32 v[52:53], v[2:3], v[64:65], v[52:53]
	v_lshlrev_b32_e32 v44, 16, v224
	v_and_b32_e32 v45, 0xffff0000, v224
	v_pk_fma_f32 v[52:53], v[10:11], v[46:47], v[52:53]
	s_nop 0
	v_pk_mul_f32 v[62:63], v[52:53], v[44:45]
	v_lshlrev_b32_e32 v44, 16, v221
	v_and_b32_e32 v45, 0xffff0000, v221
	v_pk_mul_f32 v[54:55], v[8:9], v[26:27]
	v_lshlrev_b32_e32 v52, 16, v225
	v_pk_fma_f32 v[54:55], v[4:5], v[66:67], v[54:55]
	v_and_b32_e32 v53, 0xffff0000, v225
	v_pk_fma_f32 v[54:55], v[12:13], v[44:45], v[54:55]
	s_nop 0
	v_pk_mul_f32 v[58:59], v[54:55], v[52:53]
	v_cvt_pk_bf16_f32 v53, v56, v57
	v_lshlrev_b64 v[56:57], 11, v[68:69]
	v_cvt_pk_bf16_f32 v52, v60, v61
	v_cvt_pk_bf16_f32 v54, v62, v63
	v_cvt_pk_bf16_f32 v55, v58, v59
	v_lshl_add_u64 v[56:57], v[36:37], 0, v[56:57]
	v_or_b32_e32 v68, 6, v38
	global_store_dwordx4 v[56:57], v[52:55], off
	v_ashrrev_i32_e32 v69, 31, v68
	v_or_b32_e32 v38, 7, v38
	v_mad_i64_i32 v[52:53], s[12:13], v68, s58, v[42:43]
	v_mad_i64_i32 v[52:53], s[12:13], v68, s58, v[40:41]
	v_pk_mul_f32 v[54:55], v[22:23], v[50:51]
	v_ashrrev_i32_e32 v39, 31, v38
	v_pk_fma_f32 v[32:33], v[14:15], v[32:33], v[54:55]
	v_pk_mul_f32 v[54:55], v[24:25], v[48:49]
	s_waitcnt vmcnt(9)
	v_lshlrev_b32_e32 v58, 16, v226
	v_and_b32_e32 v59, 0xffff0000, v226
	v_pk_fma_f32 v[32:33], v[18:19], v[58:59], v[32:33]
	s_waitcnt vmcnt(8)
	v_lshlrev_b32_e32 v52, 16, v230
	v_and_b32_e32 v53, 0xffff0000, v230
	v_lshlrev_b32_e32 v56, 16, v227
	v_and_b32_e32 v57, 0xffff0000, v227
	v_pk_fma_f32 v[30:31], v[16:17], v[30:31], v[54:55]
	v_pk_mul_f32 v[60:61], v[6:7], v[46:47]
	v_pk_mul_f32 v[32:33], v[32:33], v[52:53]
	v_lshlrev_b32_e32 v52, 16, v231
	v_and_b32_e32 v53, 0xffff0000, v231
	v_pk_fma_f32 v[30:31], v[20:21], v[56:57], v[30:31]
	v_lshlrev_b32_e32 v54, 16, v228
	v_and_b32_e32 v55, 0xffff0000, v228
	v_pk_fma_f32 v[28:29], v[2:3], v[28:29], v[60:61]
	v_pk_mul_f32 v[30:31], v[30:31], v[52:53]
	v_lshlrev_b32_e32 v52, 16, v232
	v_and_b32_e32 v53, 0xffff0000, v232
	v_pk_fma_f32 v[28:29], v[10:11], v[54:55], v[28:29]
	v_lshlrev_b32_e32 v60, 16, v233
	v_pk_mul_f32 v[28:29], v[28:29], v[52:53]
	v_lshlrev_b32_e32 v52, 16, v229
	v_and_b32_e32 v53, 0xffff0000, v229
	v_pk_mul_f32 v[62:63], v[8:9], v[44:45]
	v_and_b32_e32 v61, 0xffff0000, v233
	v_pk_fma_f32 v[26:27], v[4:5], v[26:27], v[62:63]
	v_cvt_pk_bf16_f32 v28, v28, v29
	v_pk_fma_f32 v[26:27], v[12:13], v[52:53], v[26:27]
	v_pk_mul_f32 v[22:23], v[22:23], v[58:59]
	v_pk_mul_f32 v[60:61], v[26:27], v[60:61]
	v_cvt_pk_bf16_f32 v27, v30, v31
	v_lshlrev_b64 v[30:31], 11, v[68:69]
	v_cvt_pk_bf16_f32 v26, v32, v33
	v_cvt_pk_bf16_f32 v29, v60, v61
	v_lshl_add_u64 v[30:31], v[36:37], 0, v[30:31]
	global_store_dwordx4 v[30:31], v[26:29], off
	v_pk_fma_f32 v[14:15], v[14:15], v[50:51], v[22:23]
	v_pk_mul_f32 v[24:25], v[24:25], v[56:57]
	v_mad_i64_i32 v[26:27], s[12:13], v38, s58, v[42:43]
	v_mad_i64_i32 v[26:27], s[12:13], v38, s58, v[40:41]
	v_pk_fma_f32 v[16:17], v[16:17], v[48:49], v[24:25]
	v_pk_mul_f32 v[6:7], v[6:7], v[54:55]
	v_pk_mul_f32 v[8:9], v[8:9], v[52:53]
	v_pk_fma_f32 v[2:3], v[2:3], v[46:47], v[6:7]
	v_pk_fma_f32 v[4:5], v[4:5], v[44:45], v[8:9]
	s_waitcnt vmcnt(8)
	v_lshlrev_b32_e32 v40, 16, v234
	v_and_b32_e32 v41, 0xffff0000, v234
	v_pk_fma_f32 v[14:15], v[18:19], v[40:41], v[14:15]
	v_lshlrev_b32_e32 v18, 16, v235
	v_and_b32_e32 v19, 0xffff0000, v235
	v_pk_fma_f32 v[16:17], v[20:21], v[18:19], v[16:17]
	v_lshlrev_b32_e32 v18, 16, v236
	v_and_b32_e32 v19, 0xffff0000, v236
	s_waitcnt vmcnt(7)
	v_lshlrev_b32_e32 v20, 16, v240
	v_and_b32_e32 v21, 0xffff0000, v240
	v_pk_fma_f32 v[2:3], v[10:11], v[18:19], v[2:3]
	v_lshlrev_b32_e32 v42, 16, v238
	v_pk_mul_f32 v[6:7], v[2:3], v[20:21]
	v_lshlrev_b32_e32 v2, 16, v237
	v_and_b32_e32 v3, 0xffff0000, v237
	v_and_b32_e32 v43, 0xffff0000, v238
	v_lshlrev_b32_e32 v22, 16, v239
	v_and_b32_e32 v23, 0xffff0000, v239
	v_lshlrev_b32_e32 v10, 16, v241
	v_and_b32_e32 v11, 0xffff0000, v241
	v_pk_fma_f32 v[2:3], v[12:13], v[2:3], v[4:5]
	v_pk_mul_f32 v[14:15], v[14:15], v[42:43]
	v_pk_mul_f32 v[16:17], v[16:17], v[22:23]
	v_pk_mul_f32 v[8:9], v[2:3], v[10:11]
	v_cvt_pk_bf16_f32 v4, v6, v7
	v_lshlrev_b64 v[6:7], 11, v[38:39]
	v_cvt_pk_bf16_f32 v2, v14, v15
	v_cvt_pk_bf16_f32 v3, v16, v17
	v_cvt_pk_bf16_f32 v5, v8, v9
	v_lshl_add_u64 v[6:7], v[36:37], 0, v[6:7]
	global_store_dwordx4 v[6:7], v[2:5], off
	s_andn2_b64 exec, exec, s[90:91]
	s_cbranch_execz .LBB0_348

.LBB0_474:
	s_or_b64 exec, exec, s[44:45]
	v_mov_b64_e32 v[2:3], s[26:27]
	s_orn2_b64 s[26:27], s[46:47], exec
	s_branch .LBB0_475
.Lsync_last_1:
	s_or_b64 exec, exec, s[22:23]
	s_add_u32 s100, s8, 0x17202400
	s_addc_u32 s101, s9, 0
	v_mov_b32_e32 v7, 0
	v_mov_b32_e32 v8, 1
	global_atomic_add v7, v8, s[100:101]
	global_atomic_add v7, v8, s[100:101] offset:256
	global_atomic_add v7, v8, s[100:101] offset:512
	global_atomic_add v7, v8, s[100:101] offset:768
	global_atomic_add v7, v8, s[100:101] offset:1024
	global_atomic_add v7, v8, s[100:101] offset:1280
	global_atomic_add v7, v8, s[100:101] offset:1536
	global_atomic_add v7, v8, s[100:101] offset:1792
	global_atomic_add v7, v8, s[100:101] offset:2048
	global_atomic_add v7, v8, s[100:101] offset:2304
	global_atomic_add v7, v8, s[100:101] offset:2560
	global_atomic_add v7, v8, s[100:101] offset:2816
	global_atomic_add v7, v8, s[100:101] offset:3072
	global_atomic_add v7, v8, s[100:101] offset:3328
	global_atomic_add v7, v8, s[100:101] offset:3584
	global_atomic_add v7, v8, s[100:101] offset:3840

.LBB0_477:
	s_or_b64 exec, exec, s[8:9]
	s_mov_b64 s[8:9], exec
	v_mbcnt_lo_u32_b32 v2, s8, 0
	v_mbcnt_hi_u32_b32 v2, s9, v2
	v_cmp_eq_u32_e32 vcc, 0, v2
	s_waitcnt vmcnt(0)
	s_and_saveexec_b64 s[12:13], vcc
	s_cbranch_execz .LBB0_111
	s_bcnt1_i32_b64 s4, s[8:9]
	v_mov_b32_e32 v2, s4
	s_branch .LBB0_111

	.amdhsa_kernel _Z8yoco_fwd4Args
		.amdhsa_group_segment_fixed_size 0
		.amdhsa_private_segment_fixed_size 0
		.amdhsa_kernarg_size 424
		.amdhsa_user_sgpr_count 2
		.amdhsa_user_sgpr_dispatch_ptr 0
		.amdhsa_user_sgpr_queue_ptr 0
		.amdhsa_user_sgpr_kernarg_segment_ptr 1
		.amdhsa_user_sgpr_dispatch_id 0
		.amdhsa_user_sgpr_kernarg_preload_length 0
		.amdhsa_user_sgpr_kernarg_preload_offset 0
		.amdhsa_user_sgpr_private_segment_size 0
		.amdhsa_uses_dynamic_stack 0
		.amdhsa_enable_private_segment 0
		.amdhsa_system_sgpr_workgroup_id_x 1
		.amdhsa_system_sgpr_workgroup_id_y 0
		.amdhsa_system_sgpr_workgroup_id_z 0
		.amdhsa_system_sgpr_workgroup_info 0
		.amdhsa_system_vgpr_workitem_id 2
		.amdhsa_next_free_vgpr 256
		.amdhsa_next_free_sgpr 102
		.amdhsa_accum_offset 256
		.amdhsa_reserve_vcc 1
		.amdhsa_float_round_mode_32 0
		.amdhsa_float_round_mode_16_64 0
		.amdhsa_float_denorm_mode_32 3
		.amdhsa_float_denorm_mode_16_64 3
		.amdhsa_dx10_clamp 1
		.amdhsa_ieee_mode 1
		.amdhsa_fp16_overflow 0
		.amdhsa_tg_split 0
		.amdhsa_exception_fp_ieee_invalid_op 0
		.amdhsa_exception_fp_denorm_src 0
		.amdhsa_exception_fp_ieee_div_zero 0
		.amdhsa_exception_fp_ieee_overflow 0
		.amdhsa_exception_fp_ieee_underflow 0
		.amdhsa_exception_fp_ieee_inexact 0
		.amdhsa_exception_int_div_zero 0
	.end_amdhsa_kernel

amdhsa.kernels:
  - .agpr_count:     0
    .args:
      - .offset:         0
        .size:           168
        .value_kind:     by_value
      - .offset:         168
        .size:           4
        .value_kind:     hidden_block_count_x
      - .offset:         172
        .size:           4
        .value_kind:     hidden_block_count_y
      - .offset:         176
        .size:           4
        .value_kind:     hidden_block_count_z
      - .offset:         180
        .size:           2
        .value_kind:     hidden_group_size_x
      - .offset:         182
        .size:           2
        .value_kind:     hidden_group_size_y
      - .offset:         184
        .size:           2
        .value_kind:     hidden_group_size_z
      - .offset:         186
        .size:           2
        .value_kind:     hidden_remainder_x
      - .offset:         188
        .size:           2
        .value_kind:     hidden_remainder_y
      - .offset:         190
        .size:           2
        .value_kind:     hidden_remainder_z
      - .offset:         208
        .size:           8
        .value_kind:     hidden_global_offset_x
      - .offset:         216
        .size:           8
        .value_kind:     hidden_global_offset_y
      - .offset:         224
        .size:           8
        .value_kind:     hidden_global_offset_z
      - .offset:         232
        .size:           2
        .value_kind:     hidden_grid_dims
      - .offset:         256
        .size:           8
        .value_kind:     hidden_multigrid_sync_arg
      - .offset:         288
        .size:           4
        .value_kind:     hidden_dynamic_lds_size
    .group_segment_fixed_size: 0
    .kernarg_segment_align: 8
    .kernarg_segment_size: 424
    .language:       OpenCL C
    .language_version:
      - 2
      - 0
    .max_flat_workgroup_size: 512
    .name:           _Z8yoco_fwd4Args
    .private_segment_fixed_size: 0
    .sgpr_count:     108
    .sgpr_spill_count: 74
    .symbol:         _Z8yoco_fwd4Args.kd
    .uniform_work_group_size: 1
    .uses_dynamic_stack: false
    .vgpr_count:     256
    .vgpr_spill_count: 0
    .wavefront_size: 64
